# prompt attention key loop: 16-lane max/sum reduction steps fused into single DPP ops (lever 7: instruction selection in a VALU-bound loop)
# baseline (speedup 1.0000x reference)
; #define LAS __attribute__((address_space(3)))
; __device__ __forceinline__ float red16_sum(float x) { x = red8_sum(x); x += dppf<0x140>(x); return x; }
; __device__ __forceinline__ float red16_max(float x) { x = fmaxf(x, dppf<0xB1>(x)); x = fmaxf(x, dppf<0x4E>(x)); x = fmaxf(x, dppf<0x141>(x)); x = fmaxf(x, dppf<0x140>(x)); return x; }
; __device__ __forceinline__ void attn_prompt_item(const Args& A, LAS unsigned char* lds, int tid, int lane, int wave, int b, int nb, int kvh) {
;     ...
;         for (int kc = kc_lo; kc < kc_hi; ++kc) {
; #pragma unroll
;             for (int mt = 0; mt < 2; ++mt) {
;                 f32x4 S[4];
; #pragma unroll
;                 for (int nt = 0; nt < 4; ++nt) {
;                     f32x4 acc = {0.f, 0.f, 0.f, 0.f};
; #pragma unroll
;                     for (int ks = 0; ks < 2; ++ks) { const bf16x8 Bk = *(const LAS bf16x8*)(lds + AT_K + (kc * 64 + nt * 16 + fr) * 144 + (ks * 32 + q4 * 8) * 2);
;                         acc = __builtin_amdgcn_mfma_f32_16x16x32_bf16(Qf[mt][ks], Bk, acc, 0, 0, 0); }
;                     S[nt] = acc;
;                 }
;                 float alpha[4];
; #pragma unroll
;                 for (int j = 0; j < 4; ++j) {
;                     const int dq = kc * 64 + fr - (tt * 32 + mt * 16 + q4 * 4 + j) - 1;
;                     float mx = -1e30f;
; #pragma unroll
;                     for (int nt = 0; nt < 4; ++nt) { const bool ok = (unsigned)(dq + nt * 16) < 128u;
;                         const float s = ok ? S[nt][j] : -1e30f; S[nt][j] = s; mx = fmaxf(mx, s); }
;                     mx = red16_max(mx);
;                     const float mn = fmaxf(mrow[mt][j], mx); alpha[j] = __builtin_amdgcn_exp2f(mrow[mt][j] - mn); mrow[mt][j] = mn;
;                     float rs = 0.f;
; #pragma unroll
;                     for (int nt = 0; nt < 4; ++nt) { const float p = __builtin_amdgcn_exp2f(S[nt][j] - mn); S[nt][j] = p; rs += p; }
;                     rs = red16_sum(rs); lrow[mt][j] = lrow[mt][j] * alpha[j] + rs;
;                 }
.LBB0_314:
	ds_read_b128 v[48:51], v214
	ds_read_b128 v[52:55], v214 offset:64
	v_subrev_u32_e32 v218, 19, v217
	v_cmp_lt_u32_e32 vcc, s57, v218
	v_subrev_u32_e32 v218, 35, v217
	s_waitcnt lgkmcnt(1)
	v_mfma_f32_16x16x32_bf16 v[48:51], v[32:35], v[48:51], 0
	v_cmp_lt_u32_e64 s[8:9], s57, v218
	v_subrev_u32_e32 v218, 51, v217
	v_cmp_lt_u32_e64 s[12:13], s57, v218
	s_waitcnt lgkmcnt(0)
	v_mfma_f32_16x16x32_bf16 v[56:59], v[40:43], v[52:55], v[48:51]
	ds_read_b128 v[52:55], v214 offset:2368
	v_add_u32_e32 v218, 0xffffffbd, v217
	v_cmp_lt_u32_e64 s[10:11], s57, v218
	ds_read_b128 v[48:51], v214 offset:2304
	s_waitcnt lgkmcnt(0)
	v_mfma_f32_16x16x32_bf16 v[48:51], v[32:35], v[48:51], 0
	s_nop 1
	v_cndmask_b32_e32 v56, v143, v56, vcc
	s_nop 0
	s_nop 0
	v_mfma_f32_16x16x32_bf16 v[60:63], v[40:43], v[52:55], v[48:51]
	ds_read_b128 v[52:55], v214 offset:4672
	s_nop 0
	s_add_i32 s78, s78, 1
	ds_read_b128 v[48:51], v214 offset:4608
	s_waitcnt lgkmcnt(0)
	v_mfma_f32_16x16x32_bf16 v[48:51], v[32:35], v[48:51], 0
	ds_read_b128 v[230:233], v214 offset:6976
	s_nop 0
	v_cndmask_b32_e64 v219, v143, v60, s[8:9]
	v_max3_f32 v60, v56, s58, v219
	v_mfma_f32_16x16x32_bf16 v[48:51], v[40:43], v[52:55], v[48:51]
	ds_read_b128 v[52:55], v214 offset:6912
	s_cmp_ge_u32 s78, s53
	s_waitcnt lgkmcnt(0)
	v_mfma_f32_16x16x32_bf16 v[52:55], v[32:35], v[52:55], 0
	s_nop 3
	v_cndmask_b32_e64 v48, v143, v48, s[12:13]
	v_mfma_f32_16x16x32_bf16 v[52:55], v[40:43], v[230:233], v[52:55]
	s_nop 0
	s_nop 0
	s_nop 5
	v_cndmask_b32_e64 v221, v143, v52, s[10:11]
	v_max3_f32 v52, v60, v48, v221
	s_nop 0
	s_nop 1
	v_max_f32_dpp v52, v52, v52 quad_perm:[1,0,3,2] row_mask:0xf bank_mask:0xf
	s_nop 0
	s_nop 0
	s_nop 0
	s_nop 1
	v_max_f32_dpp v52, v52, v52 quad_perm:[2,3,0,1] row_mask:0xf bank_mask:0xf
	s_nop 0
	s_nop 0
	s_nop 0
	s_nop 1
	v_max_f32_dpp v52, v52, v52 row_half_mirror row_mask:0xf bank_mask:0xf
	s_nop 0
	s_nop 0
	v_mov_b32_e32 v60, 0
	s_nop 1
	v_mov_b32_dpp v60, v52 row_mirror row_mask:0xf bank_mask:0xf
	v_max3_f32 v218, v172, v52, v60
	v_sub_f32_e32 v52, v172, v218
	v_exp_f32_e32 v172, v52
	v_sub_f32_e32 v52, v56, v218
	v_exp_f32_e32 v60, v52
	v_sub_f32_e32 v52, v219, v218
	v_subrev_u32_e32 v219, 18, v217
	v_cmp_lt_u32_e64 s[10:11], s57, v219
	v_subrev_u32_e32 v219, 34, v217
	v_cmp_lt_u32_e64 s[14:15], s57, v219
	v_subrev_u32_e32 v219, 50, v217
	v_sub_f32_e32 v48, v48, v218
	v_cmp_lt_u32_e64 s[18:19], s57, v219
	v_add_u32_e32 v219, 0xffffffbe, v217
	v_exp_f32_e32 v56, v52
	v_exp_f32_e32 v52, v48
	v_sub_f32_e32 v48, v221, v218
	v_cndmask_b32_e64 v57, v143, v57, s[10:11]
	v_cndmask_b32_e64 v221, v143, v61, s[14:15]
	v_cmp_lt_u32_e64 s[16:17], s57, v219
	v_max3_f32 v61, v57, s58, v221
	v_cndmask_b32_e64 v49, v143, v49, s[18:19]
	v_cndmask_b32_e64 v223, v143, v53, s[16:17]
	v_max3_f32 v53, v61, v49, v223
	s_nop 0
	v_exp_f32_e32 v48, v48
	s_nop 0
	v_max_f32_dpp v53, v53, v53 quad_perm:[1,0,3,2] row_mask:0xf bank_mask:0xf
	s_nop 0
	s_nop 0
	s_nop 0
	s_nop 1
	v_max_f32_dpp v53, v53, v53 quad_perm:[2,3,0,1] row_mask:0xf bank_mask:0xf
	s_nop 0
	s_nop 0
	s_nop 0
	s_nop 1
	v_max_f32_dpp v53, v53, v53 row_half_mirror row_mask:0xf bank_mask:0xf
	s_nop 0
	s_nop 0
	v_mov_b32_e32 v61, 0
	s_nop 1
	v_mov_b32_dpp v61, v53 row_mirror row_mask:0xf bank_mask:0xf
	v_max3_f32 v219, v173, v53, v61
	v_sub_f32_e32 v53, v173, v219
	v_exp_f32_e32 v173, v53
	v_sub_f32_e32 v53, v57, v219
	v_exp_f32_e32 v61, v53
	v_sub_f32_e32 v53, v221, v219
	v_exp_f32_e32 v57, v53
	v_sub_f32_e32 v49, v49, v219
	v_exp_f32_e32 v53, v49
	v_sub_f32_e32 v49, v223, v219
	v_exp_f32_e32 v49, v49
	v_pk_add_f32 v[224:225], v[60:61], 0 op_sel_hi:[1,0]
	v_subrev_u32_e32 v221, 17, v217
	v_pk_add_f32 v[224:225], v[56:57], v[224:225]
	v_cmp_lt_u32_e64 s[16:17], s57, v221
	v_pk_add_f32 v[224:225], v[52:53], v[224:225]
	v_subrev_u32_e32 v221, 33, v217
	v_pk_add_f32 v[224:225], v[48:49], v[224:225]
	v_subrev_u32_e32 v223, 49, v217
	v_cmp_lt_u32_e64 s[20:21], s57, v221
	v_add_f32_dpp v224, v224, v224 quad_perm:[1,0,3,2] row_mask:0xf bank_mask:0xf
	v_add_f32_dpp v225, v225, v225 quad_perm:[1,0,3,2] row_mask:0xf bank_mask:0xf
	s_nop 0
	s_nop 0
	s_nop 0
	v_cmp_lt_u32_e64 s[22:23], s57, v223
	v_add_f32_dpp v224, v224, v224 quad_perm:[2,3,0,1] row_mask:0xf bank_mask:0xf
	v_add_f32_dpp v225, v225, v225 quad_perm:[2,3,0,1] row_mask:0xf bank_mask:0xf
	s_nop 0
	s_nop 0
	s_nop 0
	v_add_u32_e32 v223, 0xffffffbf, v217
	v_add_f32_dpp v224, v224, v224 row_half_mirror row_mask:0xf bank_mask:0xf
	v_add_f32_dpp v225, v225, v225 row_half_mirror row_mask:0xf bank_mask:0xf
	s_nop 0
	s_nop 0
	s_nop 0
	v_cndmask_b32_e64 v58, v143, v58, s[16:17]
	v_add_f32_dpp v224, v224, v224 row_mirror row_mask:0xf bank_mask:0xf
	v_add_f32_dpp v225, v225, v225 row_mirror row_mask:0xf bank_mask:0xf
	s_nop 0
	v_cndmask_b32_e64 v221, v143, v62, s[20:21]
	v_cmp_lt_u32_e64 s[24:25], s57, v223
	v_pk_fma_f32 v[170:171], v[170:171], v[172:173], v[224:225]
	v_max3_f32 v62, v58, s58, v221
	v_cndmask_b32_e64 v50, v143, v50, s[22:23]
	v_cndmask_b32_e64 v224, v143, v54, s[24:25]
	v_max3_f32 v54, v62, v50, v224
	s_nop 0
	v_subrev_u32_e32 v230, 64, v217
	v_cmp_lt_u32_e64 s[34:35], s57, v230
	v_max_f32_dpp v54, v54, v54 quad_perm:[1,0,3,2] row_mask:0xf bank_mask:0xf
	s_nop 0
	s_nop 0
	s_nop 0
	v_cvt_pk_bf16_f32 v60, v60, s0
	v_cvt_pk_bf16_f32 v56, v56, s0
	v_max_f32_dpp v54, v54, v54 quad_perm:[2,3,0,1] row_mask:0xf bank_mask:0xf
	s_nop 0
	s_nop 0
	s_nop 0
	v_cvt_pk_bf16_f32 v52, v52, s0
	v_cvt_pk_bf16_f32 v48, v48, s0
	v_max_f32_dpp v54, v54, v54 row_half_mirror row_mask:0xf bank_mask:0xf
	s_nop 0
	s_nop 0
	v_mov_b32_e32 v62, 0
	ds_write_b16 v85, v60
	v_cvt_pk_bf16_f32 v60, v61, s0
; #define LAS __attribute__((address_space(3)))
; __device__ __forceinline__ unsigned f2bf(float f) { return pk2(f, 0.f) & 0xffffu; }
; __device__ __forceinline__ float red16_sum(float x) { x = red8_sum(x); x += dppf<0x140>(x); return x; }
; __device__ __forceinline__ float red16_max(float x) { x = fmaxf(x, dppf<0xB1>(x)); x = fmaxf(x, dppf<0x4E>(x)); x = fmaxf(x, dppf<0x141>(x)); x = fmaxf(x, dppf<0x140>(x)); return x; }
; __device__ __forceinline__ void attn_prompt_item(const Args& A, LAS unsigned char* lds, int tid, int lane, int wave, int b, int nb, int kvh) {
;     ...
;                 for (int j = 0; j < 4; ++j) {
;                     const int dq = kc * 64 + fr - (tt * 32 + mt * 16 + q4 * 4 + j) - 1;
;                     float mx = -1e30f;
; #pragma unroll
;                     for (int nt = 0; nt < 4; ++nt) { const bool ok = (unsigned)(dq + nt * 16) < 128u;
;                         const float s = ok ? S[nt][j] : -1e30f; S[nt][j] = s; mx = fmaxf(mx, s); }
;                     mx = red16_max(mx);
;                     const float mn = fmaxf(mrow[mt][j], mx); alpha[j] = __builtin_amdgcn_exp2f(mrow[mt][j] - mn); mrow[mt][j] = mn;
;                     float rs = 0.f;
; #pragma unroll
;                     for (int nt = 0; nt < 4; ++nt) { const float p = __builtin_amdgcn_exp2f(S[nt][j] - mn); S[nt][j] = p; rs += p; }
;                     rs = red16_sum(rs); lrow[mt][j] = lrow[mt][j] * alpha[j] + rs;
;                 }
; #pragma unroll
;                 for (int dt = 0; dt < 4; ++dt)
; #pragma unroll
;                     for (int j = 0; j < 4; ++j) O[mt][dt][j] *= alpha[j];
; #pragma unroll
;                 for (int nt = 0; nt < 4; ++nt)
; #pragma unroll
;                     for (int j = 0; j < 4; ++j) *(LAS unsigned short*)(Pw + (q4 * 4 + j) * 144 + (nt * 16 + fr) * 2) = (unsigned short)f2bf(S[nt][j]);
;                 LDS_WAIT();
;                 bf16x8 Pa[2];
; #pragma unroll
;                 for (int ks = 0; ks < 2; ++ks) Pa[ks] = *(const LAS bf16x8*)(Pw + fr * 144 + (ks * 32 + q4 * 8) * 2);
; #pragma unroll
;                 for (int dt = 0; dt < 4; ++dt)
; #pragma unroll
;                     for (int ks = 0; ks < 2; ++ks) { const bf16x8 Bv = *(const LAS bf16x8*)(lds + AT_V + (dt * 16 + fr) * 528 + (kc * 64 + ks * 32 + q4 * 8) * 2);
;                         O[mt][dt] = __builtin_amdgcn_mfma_f32_16x16x32_bf16(Pa[ks], Bv, O[mt][dt], 0, 0, 0); }
	v_mov_b32_dpp v62, v54 row_mirror row_mask:0xf bank_mask:0xf
	v_max3_f32 v223, v174, v54, v62
	v_sub_f32_e32 v54, v174, v223
	v_exp_f32_e32 v174, v54
	v_sub_f32_e32 v54, v58, v223
	v_exp_f32_e32 v62, v54
	v_sub_f32_e32 v54, v221, v223
	v_add_u32_e32 v221, -16, v217
	v_sub_f32_e32 v50, v50, v223
	v_cmp_lt_u32_e64 s[24:25], s57, v221
	v_subrev_u32_e32 v221, 32, v217
	v_exp_f32_e32 v58, v54
	v_exp_f32_e32 v54, v50
	v_sub_f32_e32 v50, v224, v223
	v_cmp_lt_u32_e64 s[26:27], s57, v221
	v_subrev_u32_e32 v224, 48, v217
	v_cndmask_b32_e64 v59, v143, v59, s[24:25]
	v_cndmask_b32_e64 v221, v143, v63, s[26:27]
	v_cmp_lt_u32_e64 s[28:29], s57, v224
	v_max3_f32 v63, v59, s58, v221
	v_cndmask_b32_e64 v224, v143, v55, s[34:35]
	v_cndmask_b32_e64 v51, v143, v51, s[28:29]
	v_max3_f32 v55, v63, v51, v224
	s_nop 0
	v_exp_f32_e32 v50, v50
	ds_write_b16 v85, v56 offset:32
	v_max_f32_dpp v55, v55, v55 quad_perm:[1,0,3,2] row_mask:0xf bank_mask:0xf
	s_nop 0
	s_nop 0
	s_nop 0
	v_cvt_pk_bf16_f32 v56, v57, s0
	ds_write_b16 v85, v52 offset:64
	v_max_f32_dpp v55, v55, v55 quad_perm:[2,3,0,1] row_mask:0xf bank_mask:0xf
	s_nop 0
	s_nop 0
	s_nop 0
	v_cvt_pk_bf16_f32 v52, v53, s0
	ds_write_b16 v85, v48 offset:96
	v_max_f32_dpp v55, v55, v55 row_half_mirror row_mask:0xf bank_mask:0xf
	s_nop 0
	s_nop 0
	v_mov_b32_e32 v63, 0
	v_cvt_pk_bf16_f32 v48, v49, s0
	ds_write_b16 v85, v60 offset:144
	v_mov_b32_dpp v63, v55 row_mirror row_mask:0xf bank_mask:0xf
	v_max3_f32 v225, v175, v55, v63
	v_sub_f32_e32 v55, v175, v225
	v_exp_f32_e32 v175, v55
	v_sub_f32_e32 v55, v59, v225
	v_exp_f32_e32 v63, v55
	v_sub_f32_e32 v55, v221, v225
	v_sub_f32_e32 v51, v51, v225
	v_exp_f32_e32 v59, v55
	v_exp_f32_e32 v55, v51
	v_sub_f32_e32 v51, v224, v225
	v_exp_f32_e32 v51, v51
	v_cvt_pk_bf16_f32 v60, v62, s0
	ds_write_b16 v85, v56 offset:176
	v_cvt_pk_bf16_f32 v56, v58, s0
	ds_write_b16 v85, v52 offset:208
	v_cvt_pk_bf16_f32 v52, v54, s0
	ds_write_b16 v85, v48 offset:240
	v_cvt_pk_bf16_f32 v48, v50, s0
	v_pk_add_f32 v[232:233], v[62:63], 0 op_sel_hi:[1,0]
	ds_write_b16 v85, v60 offset:288
	v_cvt_pk_bf16_f32 v60, v63, s0
	ds_write_b16 v85, v56 offset:320
	v_cvt_pk_bf16_f32 v56, v59, s0
	ds_write_b16 v85, v52 offset:352
	v_cvt_pk_bf16_f32 v52, v55, s0
	ds_write_b16 v85, v48 offset:384
	v_cvt_pk_bf16_f32 v48, v51, s0
	v_pk_add_f32 v[232:233], v[58:59], v[232:233]
	ds_write_b16 v85, v60 offset:432
	ds_write_b16 v85, v56 offset:464
	ds_write_b16 v85, v52 offset:496
	ds_write_b16 v85, v48 offset:528
	v_pk_add_f32 v[232:233], v[54:55], v[232:233]
	s_waitcnt lgkmcnt(0)
	v_pk_mul_f32 v[30:31], v[30:31], v[174:175]
	v_pk_add_f32 v[232:233], v[50:51], v[232:233]
	ds_read_b128 v[48:51], v91
	ds_read_b128 v[52:55], v91 offset:64
	ds_read_b128 v[56:59], v215
	v_pk_mul_f32 v[28:29], v[28:29], v[172:173]
	v_pk_mul_f32 v[26:27], v[26:27], v[174:175]
	v_pk_mul_f32 v[24:25], v[24:25], v[172:173]
	s_waitcnt lgkmcnt(0)
	v_mfma_f32_16x16x32_bf16 v[28:31], v[48:51], v[56:59], v[28:31]
	ds_read_b128 v[56:59], v215 offset:64
	v_pk_mul_f32 v[22:23], v[22:23], v[174:175]
	v_pk_mul_f32 v[20:21], v[20:21], v[172:173]
	s_waitcnt lgkmcnt(0)
	v_mfma_f32_16x16x32_bf16 v[28:31], v[52:55], v[56:59], v[28:31]
	ds_read_b128 v[56:59], v215 offset:8448
	v_pk_mul_f32 v[18:19], v[18:19], v[174:175]
	v_pk_mul_f32 v[16:17], v[16:17], v[172:173]
	s_waitcnt lgkmcnt(0)
	v_mfma_f32_16x16x32_bf16 v[24:27], v[48:51], v[56:59], v[24:27]
	ds_read_b128 v[56:59], v215 offset:8512
	v_add_f32_dpp v232, v232, v232 quad_perm:[1,0,3,2] row_mask:0xf bank_mask:0xf
	v_add_f32_dpp v233, v233, v233 quad_perm:[1,0,3,2] row_mask:0xf bank_mask:0xf
	s_waitcnt lgkmcnt(0)
	v_mfma_f32_16x16x32_bf16 v[24:27], v[52:55], v[56:59], v[24:27]
	ds_read_b128 v[56:59], v215 offset:16896
	s_nop 0
	v_mov_b32_e32 v234, 0
	s_waitcnt lgkmcnt(0)
	v_mfma_f32_16x16x32_bf16 v[20:23], v[48:51], v[56:59], v[20:23]
	ds_read_b128 v[56:59], v215 offset:16960
	v_mov_b32_e32 v235, 0
	v_mov_b32_dpp v234, v232 quad_perm:[2,3,0,1] row_mask:0xf bank_mask:0xf
	s_waitcnt lgkmcnt(0)
	v_mfma_f32_16x16x32_bf16 v[20:23], v[52:55], v[56:59], v[20:23]
	ds_read_b128 v[56:59], v216
	v_mov_b32_dpp v235, v233 quad_perm:[2,3,0,1] row_mask:0xf bank_mask:0xf
	v_pk_add_f32 v[232:233], v[232:233], v[234:235]
	s_waitcnt lgkmcnt(0)
	v_mfma_f32_16x16x32_bf16 v[16:19], v[48:51], v[56:59], v[16:19]
	ds_read_b128 v[48:51], v216 offset:64
	s_waitcnt lgkmcnt(0)
	ds_read_b128 v[56:59], v214 offset:2368
	s_waitcnt lgkmcnt(1)
	v_mfma_f32_16x16x32_bf16 v[16:19], v[52:55], v[48:51], v[16:19]
	ds_read_b128 v[48:51], v214
	ds_read_b128 v[52:55], v214 offset:64
	ds_read_b128 v[60:63], v214 offset:4672
	s_waitcnt lgkmcnt(2)
	v_mfma_f32_16x16x32_bf16 v[48:51], v[36:39], v[48:51], 0
	v_mov_b32_e32 v234, 0
	v_mov_b32_e32 v235, 0
	s_waitcnt lgkmcnt(1)
	v_mfma_f32_16x16x32_bf16 v[48:51], v[44:47], v[52:55], v[48:51]
	ds_read_b128 v[52:55], v214 offset:2304
	v_mov_b32_dpp v234, v232 row_half_mirror row_mask:0xf bank_mask:0xf
	v_mov_b32_dpp v235, v233 row_half_mirror row_mask:0xf bank_mask:0xf
	s_waitcnt lgkmcnt(0)
	v_mfma_f32_16x16x32_bf16 v[52:55], v[36:39], v[52:55], 0
	v_add_f32_e64 v232, v232, v234
	v_add_f32_e64 v233, v233, v235
	v_mov_b32_e32 v234, 0
	v_mov_b32_e32 v235, 0
	v_mfma_f32_16x16x32_bf16 v[52:55], v[44:47], v[56:59], v[52:55]
	ds_read_b128 v[56:59], v214 offset:4608
	v_mov_b32_dpp v234, v232 row_mirror row_mask:0xf bank_mask:0xf
	v_mov_b32_dpp v235, v233 row_mirror row_mask:0xf bank_mask:0xf
	s_waitcnt lgkmcnt(0)
; #define LAS __attribute__((address_space(3)))
; __device__ __forceinline__ unsigned f2bf(float f) { return pk2(f, 0.f) & 0xffffu; }
; __device__ __forceinline__ float red16_sum(float x) { x = red8_sum(x); x += dppf<0x140>(x); return x; }
; __device__ __forceinline__ float red16_max(float x) { x = fmaxf(x, dppf<0xB1>(x)); x = fmaxf(x, dppf<0x4E>(x)); x = fmaxf(x, dppf<0x141>(x)); x = fmaxf(x, dppf<0x140>(x)); return x; }
; __device__ __forceinline__ void attn_prompt_item(const Args& A, LAS unsigned char* lds, int tid, int lane, int wave, int b, int nb, int kvh) {
;     ...
;                 float alpha[4];
; #pragma unroll
;                 for (int j = 0; j < 4; ++j) {
;                     const int dq = kc * 64 + fr - (tt * 32 + mt * 16 + q4 * 4 + j) - 1;
;                     float mx = -1e30f;
; #pragma unroll
;                     for (int nt = 0; nt < 4; ++nt) { const bool ok = (unsigned)(dq + nt * 16) < 128u;
;                         const float s = ok ? S[nt][j] : -1e30f; S[nt][j] = s; mx = fmaxf(mx, s); }
;                     mx = red16_max(mx);
;                     const float mn = fmaxf(mrow[mt][j], mx); alpha[j] = __builtin_amdgcn_exp2f(mrow[mt][j] - mn); mrow[mt][j] = mn;
;                     float rs = 0.f;
; #pragma unroll
;                     for (int nt = 0; nt < 4; ++nt) { const float p = __builtin_amdgcn_exp2f(S[nt][j] - mn); S[nt][j] = p; rs += p; }
;                     rs = red16_sum(rs); lrow[mt][j] = lrow[mt][j] * alpha[j] + rs;
;                 }
; #pragma unroll
;                 for (int dt = 0; dt < 4; ++dt)
; #pragma unroll
;                     for (int j = 0; j < 4; ++j) O[mt][dt][j] *= alpha[j];
; #pragma unroll
;                 for (int nt = 0; nt < 4; ++nt)
; #pragma unroll
;                     for (int j = 0; j < 4; ++j) *(LAS unsigned short*)(Pw + (q4 * 4 + j) * 144 + (nt * 16 + fr) * 2) = (unsigned short)f2bf(S[nt][j]);
	v_mfma_f32_16x16x32_bf16 v[56:59], v[36:39], v[56:59], 0
	v_add_f32_e64 v232, v232, v234
	v_add_f32_e64 v233, v233, v235
	s_nop 0
	v_cndmask_b32_e32 v52, v143, v52, vcc
	v_pk_fma_f32 v[168:169], v[168:169], v[174:175], v[232:233]
	v_mfma_f32_16x16x32_bf16 v[56:59], v[44:47], v[60:63], v[56:59]
	ds_read_b128 v[60:63], v214 offset:6912
	ds_read_b128 v[172:175], v214 offset:6976
	v_cndmask_b32_e64 v53, v143, v53, s[10:11]
	s_waitcnt lgkmcnt(1)
	v_mfma_f32_16x16x32_bf16 v[60:63], v[36:39], v[60:63], 0
	v_cndmask_b32_e64 v54, v143, v54, s[16:17]
	v_cndmask_b32_e64 v55, v143, v55, s[24:25]
	s_nop 0
	s_waitcnt lgkmcnt(0)
	v_mfma_f32_16x16x32_bf16 v[60:63], v[44:47], v[172:175], v[60:63]
	v_add_u32_e32 v172, -3, v217
	v_cmp_lt_u32_e64 s[34:35], s57, v172
	v_cndmask_b32_e64 v173, v143, v56, s[8:9]
	s_nop 0
	v_cndmask_b32_e64 v48, v143, v48, s[34:35]
	v_max3_f32 v172, v48, s58, v52
	s_nop 1
	v_cndmask_b32_e64 v174, v143, v60, s[12:13]
	v_max3_f32 v56, v172, v173, v174
	s_nop 0
	v_cndmask_b32_e64 v175, v143, v61, s[18:19]
	s_nop 0
	v_max_f32_dpp v56, v56, v56 quad_perm:[1,0,3,2] row_mask:0xf bank_mask:0xf
	s_nop 0
	s_nop 0
	s_nop 0
	v_add_u32_e32 v214, 0x2400, v214
	s_nop 0
	v_max_f32_dpp v56, v56, v56 quad_perm:[2,3,0,1] row_mask:0xf bank_mask:0xf
	s_nop 0
	s_nop 0
	s_nop 0
	s_nop 1
	v_max_f32_dpp v56, v56, v56 row_half_mirror row_mask:0xf bank_mask:0xf
	s_nop 0
	s_nop 0
	v_mov_b32_e32 v60, 0
	s_nop 1
	v_mov_b32_dpp v60, v56 row_mirror row_mask:0xf bank_mask:0xf
	v_max3_f32 v221, v228, v56, v60
	v_sub_f32_e32 v48, v48, v221
	v_sub_f32_e32 v56, v228, v221
	v_exp_f32_e32 v60, v48
	v_sub_f32_e32 v48, v52, v221
	v_exp_f32_e32 v172, v56
	v_exp_f32_e32 v56, v48
	v_sub_f32_e32 v48, v173, v221
	v_add_u32_e32 v173, -2, v217
	v_cmp_lt_u32_e32 vcc, s57, v173
	v_exp_f32_e32 v52, v48
	v_sub_f32_e32 v48, v174, v221
	v_cndmask_b32_e32 v49, v143, v49, vcc
	v_max3_f32 v173, v49, s58, v53
	v_cndmask_b32_e64 v174, v143, v57, s[14:15]
	v_max3_f32 v57, v173, v174, v175
	v_exp_f32_e32 v48, v48
	v_mov_b32_e32 v228, v221
	v_max_f32_dpp v57, v57, v57 quad_perm:[1,0,3,2] row_mask:0xf bank_mask:0xf
	s_nop 0
	s_nop 0
	s_nop 0
	s_nop 1
	v_max_f32_dpp v57, v57, v57 quad_perm:[2,3,0,1] row_mask:0xf bank_mask:0xf
	s_nop 0
	s_nop 0
	s_nop 0
	s_nop 1
	v_max_f32_dpp v57, v57, v57 row_half_mirror row_mask:0xf bank_mask:0xf
	s_nop 0
	s_nop 0
	v_mov_b32_e32 v61, 0
	s_nop 1
	v_mov_b32_dpp v61, v57 row_mirror row_mask:0xf bank_mask:0xf
	v_max3_f32 v224, v226, v57, v61
	v_sub_f32_e32 v49, v49, v224
	v_sub_f32_e32 v57, v226, v224
	v_exp_f32_e32 v61, v49
	v_sub_f32_e32 v49, v53, v224
	v_exp_f32_e32 v173, v57
	v_exp_f32_e32 v57, v49
	v_sub_f32_e32 v49, v174, v224
	v_exp_f32_e32 v53, v49
	v_sub_f32_e32 v49, v175, v224
	v_exp_f32_e32 v49, v49
	v_pk_add_f32 v[174:175], v[60:61], 0 op_sel_hi:[1,0]
	s_nop 0
	v_pk_add_f32 v[174:175], v[56:57], v[174:175]
	v_cvt_pk_bf16_f32 v60, v60, s0
	v_pk_add_f32 v[174:175], v[52:53], v[174:175]
	v_cvt_pk_bf16_f32 v56, v56, s0
	v_pk_add_f32 v[174:175], v[48:49], v[174:175]
	v_cvt_pk_bf16_f32 v52, v52, s0
	v_cvt_pk_bf16_f32 v48, v48, s0
	v_add_f32_dpp v174, v174, v174 quad_perm:[1,0,3,2] row_mask:0xf bank_mask:0xf
	v_add_f32_dpp v175, v175, v175 quad_perm:[1,0,3,2] row_mask:0xf bank_mask:0xf
	s_nop 0
	s_nop 0
	s_nop 0
	ds_write_b16 v85, v60
	v_add_f32_dpp v174, v174, v174 quad_perm:[2,3,0,1] row_mask:0xf bank_mask:0xf
	v_add_f32_dpp v175, v175, v175 quad_perm:[2,3,0,1] row_mask:0xf bank_mask:0xf
	s_nop 0
	s_nop 0
	s_nop 0
	v_cvt_pk_bf16_f32 v60, v61, s0
	v_add_f32_dpp v174, v174, v174 row_half_mirror row_mask:0xf bank_mask:0xf
	v_add_f32_dpp v175, v175, v175 row_half_mirror row_mask:0xf bank_mask:0xf
	s_nop 0
	s_nop 0
	s_nop 0
	ds_write_b16 v85, v56 offset:32
	v_add_f32_dpp v174, v174, v174 row_mirror row_mask:0xf bank_mask:0xf
	v_add_f32_dpp v175, v175, v175 row_mirror row_mask:0xf bank_mask:0xf
	s_nop 0
	v_cndmask_b32_e64 v226, v143, v62, s[22:23]
	v_pk_fma_f32 v[166:167], v[166:167], v[172:173], v[174:175]
	v_add_u32_e32 v174, -1, v217
	v_cmp_lt_u32_e32 vcc, s57, v174
	v_cndmask_b32_e64 v175, v143, v58, s[20:21]
	s_nop 0
	v_cndmask_b32_e32 v50, v143, v50, vcc
	v_max3_f32 v174, v50, s58, v54
	v_max3_f32 v58, v174, v175, v226
	v_cmp_lt_u32_e32 vcc, s57, v217
	v_cndmask_b32_e64 v217, v143, v59, s[26:27]
	v_max_f32_dpp v58, v58, v58 quad_perm:[1,0,3,2] row_mask:0xf bank_mask:0xf
	s_nop 0
	s_nop 0
	s_nop 0
	v_cndmask_b32_e32 v51, v143, v51, vcc
	v_cvt_pk_bf16_f32 v56, v57, s0
	v_max_f32_dpp v58, v58, v58 quad_perm:[2,3,0,1] row_mask:0xf bank_mask:0xf
	s_nop 0
	s_nop 0
	s_nop 0
	ds_write_b16 v85, v52 offset:64
	v_cvt_pk_bf16_f32 v52, v53, s0
	v_max_f32_dpp v58, v58, v58 row_half_mirror row_mask:0xf bank_mask:0xf
	s_nop 0
	s_nop 0
	v_mov_b32_e32 v62, 0
	ds_write_b16 v85, v48 offset:96
	v_cvt_pk_bf16_f32 v48, v49, s0
	v_mov_b32_dpp v62, v58 row_mirror row_mask:0xf bank_mask:0xf
	v_max3_f32 v227, v222, v58, v62
	v_sub_f32_e32 v50, v50, v227
	v_sub_f32_e32 v58, v222, v227
	v_exp_f32_e32 v62, v50
	v_sub_f32_e32 v50, v54, v227
	v_exp_f32_e32 v174, v58
	v_exp_f32_e32 v58, v50
	v_sub_f32_e32 v50, v175, v227
	v_max3_f32 v175, v51, s58, v55
	v_cndmask_b32_e64 v222, v143, v63, s[28:29]
	v_max3_f32 v59, v175, v217, v222
	s_nop 0
	v_exp_f32_e32 v54, v50
	v_sub_f32_e32 v50, v226, v227
	v_max_f32_dpp v59, v59, v59 quad_perm:[1,0,3,2] row_mask:0xf bank_mask:0xf
	s_nop 0
	s_nop 0
	s_nop 0
	v_exp_f32_e32 v50, v50
	ds_write_b16 v85, v60 offset:144
	v_max_f32_dpp v59, v59, v59 quad_perm:[2,3,0,1] row_mask:0xf bank_mask:0xf
	s_nop 0
	s_nop 0
	s_nop 0
	v_cvt_pk_bf16_f32 v60, v62, s0
	ds_write_b16 v85, v56 offset:176
	v_max_f32_dpp v59, v59, v59 row_half_mirror row_mask:0xf bank_mask:0xf
	s_nop 0
	s_nop 0
	v_mov_b32_e32 v63, 0
	v_cvt_pk_bf16_f32 v56, v58, s0
	ds_write_b16 v85, v52 offset:208
	v_mov_b32_dpp v63, v59 row_mirror row_mask:0xf bank_mask:0xf
	v_max3_f32 v229, v220, v59, v63
	v_sub_f32_e32 v51, v51, v229
	v_sub_f32_e32 v59, v220, v229
	v_exp_f32_e32 v63, v51
	v_sub_f32_e32 v51, v55, v229
	v_exp_f32_e32 v175, v59
	v_exp_f32_e32 v59, v51
	v_sub_f32_e32 v51, v217, v229
	v_exp_f32_e32 v55, v51
	v_sub_f32_e32 v51, v222, v229
	v_exp_f32_e32 v51, v51
	v_cvt_pk_bf16_f32 v52, v54, s0
	ds_write_b16 v85, v48 offset:240
	v_cvt_pk_bf16_f32 v48, v50, s0
	v_pk_add_f32 v[232:233], v[62:63], 0 op_sel_hi:[1,0]
	ds_write_b16 v85, v60 offset:288
	v_cvt_pk_bf16_f32 v60, v63, s0
	ds_write_b16 v85, v56 offset:320
	v_cvt_pk_bf16_f32 v56, v59, s0
	ds_write_b16 v85, v52 offset:352
	v_cvt_pk_bf16_f32 v52, v55, s0
	ds_write_b16 v85, v48 offset:384
	v_cvt_pk_bf16_f32 v48, v51, s0
	v_pk_add_f32 v[232:233], v[58:59], v[232:233]
	ds_write_b16 v85, v60 offset:432
	ds_write_b16 v85, v56 offset:464
	ds_write_b16 v85, v52 offset:496
	ds_write_b16 v85, v48 offset:528
	v_pk_add_f32 v[232:233], v[54:55], v[232:233]
	s_waitcnt lgkmcnt(0)
; #define LAS __attribute__((address_space(3)))
; __device__ __forceinline__ unsigned f2bf(float f) { return pk2(f, 0.f) & 0xffffu; }
; __device__ __forceinline__ float siluf_(float x) { return x * __builtin_amdgcn_rcpf(1.f + __expf(-x)); }
; #define LDS_WAIT() asm volatile("s_waitcnt lgkmcnt(0)" ::: "memory")
; __device__ __forceinline__ void attn_prompt_item(const Args& A, LAS unsigned char* lds, int tid, int lane, int wave, int b, int nb, int kvh) {
;     ...
; #pragma unroll
;                 for (int dt = 0; dt < 4; ++dt)
; #pragma unroll
;                     for (int j = 0; j < 4; ++j) O[mt][dt][j] *= alpha[j];
; #pragma unroll
;                 for (int nt = 0; nt < 4; ++nt)
; #pragma unroll
;                     for (int j = 0; j < 4; ++j) *(LAS unsigned short*)(Pw + (q4 * 4 + j) * 144 + (nt * 16 + fr) * 2) = (unsigned short)f2bf(S[nt][j]);
;                 LDS_WAIT();
;                 bf16x8 Pa[2];
; #pragma unroll
;                 for (int ks = 0; ks < 2; ++ks) Pa[ks] = *(const LAS bf16x8*)(Pw + fr * 144 + (ks * 32 + q4 * 8) * 2);
; #pragma unroll
;                 for (int dt = 0; dt < 4; ++dt)
; #pragma unroll
;                     for (int ks = 0; ks < 2; ++ks) { const bf16x8 Bv = *(const LAS bf16x8*)(lds + AT_V + (dt * 16 + fr) * 528 + (kc * 64 + ks * 32 + q4 * 8) * 2);
;                         O[mt][dt] = __builtin_amdgcn_mfma_f32_16x16x32_bf16(Pa[ks], Bv, O[mt][dt], 0, 0, 0); }
;                 LDS_WAIT();
;             }
;         }
; #pragma unroll
;         for (int mt = 0; mt < 2; ++mt)
; #pragma unroll
;             for (int j = 0; j < 4; ++j) {
;                 const int tq = tt * 32 + mt * 16 + q4 * 4 + j; const size_t row = (size_t)b * SEQ + nb * 128 + tq; const float il = __builtin_amdgcn_rcpf(lrow[mt][j]);
; #pragma unroll
;                 for (int dt = 0; dt < 4; ++dt) { const int d = dt * 16 + fr; const float g = bf2f(gts[mt][j][dt]);
;                     MIX[row * DM + 512 + hq * 64 + d] = (bf16_t)f2bf(O[mt][dt][j] * il * siluf_(g)); }
	v_pk_mul_f32 v[14:15], v[14:15], v[174:175]
	v_pk_add_f32 v[232:233], v[50:51], v[232:233]
	ds_read_b128 v[48:51], v91
	ds_read_b128 v[52:55], v91 offset:64
	ds_read_b128 v[56:59], v215
	v_pk_mul_f32 v[12:13], v[12:13], v[172:173]
	v_pk_mul_f32 v[10:11], v[10:11], v[174:175]
	v_pk_mul_f32 v[8:9], v[8:9], v[172:173]
	s_waitcnt lgkmcnt(0)
	v_mfma_f32_16x16x32_bf16 v[12:15], v[48:51], v[56:59], v[12:15]
	ds_read_b128 v[56:59], v215 offset:64
	v_pk_mul_f32 v[6:7], v[6:7], v[174:175]
	v_pk_mul_f32 v[4:5], v[4:5], v[172:173]
	s_waitcnt lgkmcnt(0)
	v_mfma_f32_16x16x32_bf16 v[12:15], v[52:55], v[56:59], v[12:15]
	ds_read_b128 v[56:59], v215 offset:8448
	v_pk_mul_f32 v[2:3], v[2:3], v[174:175]
	v_pk_mul_f32 v[0:1], v[0:1], v[172:173]
	s_waitcnt lgkmcnt(0)
	v_mfma_f32_16x16x32_bf16 v[8:11], v[48:51], v[56:59], v[8:11]
	ds_read_b128 v[56:59], v215 offset:8512
	v_add_f32_dpp v232, v232, v232 quad_perm:[1,0,3,2] row_mask:0xf bank_mask:0xf
	v_add_f32_dpp v233, v233, v233 quad_perm:[1,0,3,2] row_mask:0xf bank_mask:0xf
	s_waitcnt lgkmcnt(0)
	v_mfma_f32_16x16x32_bf16 v[8:11], v[52:55], v[56:59], v[8:11]
	ds_read_b128 v[56:59], v215 offset:16896
	s_nop 0
	v_mov_b32_e32 v234, 0
	s_waitcnt lgkmcnt(0)
	v_mfma_f32_16x16x32_bf16 v[4:7], v[48:51], v[56:59], v[4:7]
	ds_read_b128 v[56:59], v215 offset:16960
	v_mov_b32_e32 v235, 0
	v_mov_b32_dpp v234, v232 quad_perm:[2,3,0,1] row_mask:0xf bank_mask:0xf
	s_waitcnt lgkmcnt(0)
	v_mfma_f32_16x16x32_bf16 v[4:7], v[52:55], v[56:59], v[4:7]
	ds_read_b128 v[56:59], v216
	v_mov_b32_dpp v235, v233 quad_perm:[2,3,0,1] row_mask:0xf bank_mask:0xf
	v_pk_add_f32 v[232:233], v[232:233], v[234:235]
	s_waitcnt lgkmcnt(0)
	v_mfma_f32_16x16x32_bf16 v[0:3], v[48:51], v[56:59], v[0:3]
	ds_read_b128 v[48:51], v216 offset:64
	s_nop 0
	s_nop 0
	s_waitcnt lgkmcnt(0)
	v_mfma_f32_16x16x32_bf16 v[0:3], v[52:55], v[48:51], v[0:3]
	v_add_f32_dpp v232, v232, v232 row_half_mirror row_mask:0xf bank_mask:0xf
	v_add_f32_dpp v233, v233, v233 row_half_mirror row_mask:0xf bank_mask:0xf
	s_nop 0
	s_nop 0
	s_nop 0
	s_waitcnt lgkmcnt(0)
	v_add_u32_e32 v216, 0x80, v216
	v_add_f32_dpp v232, v232, v232 row_mirror row_mask:0xf bank_mask:0xf
	v_add_f32_dpp v233, v233, v233 row_mirror row_mask:0xf bank_mask:0xf
	s_nop 0
	v_add_u32_e32 v215, 0x80, v215
	v_pk_fma_f32 v[164:165], v[164:165], v[174:175], v[232:233]
	v_mov_b32_e32 v217, v230
	v_mov_b32_e32 v172, v218
	v_mov_b32_e32 v173, v219
	v_mov_b32_e32 v174, v223
	v_mov_b32_e32 v175, v225
	v_mov_b32_e32 v226, v224
	v_mov_b32_e32 v222, v227
	v_mov_b32_e32 v220, v229
	s_cbranch_scc0 .LBB0_314
	s_waitcnt vmcnt(31)
	v_lshlrev_b32_e32 v34, 16, v213
	v_mul_f32_e32 v32, 0xbfb8aa3b, v34
	v_exp_f32_e32 v32, v32
	s_waitcnt vmcnt(30)
	v_lshlrev_b32_e32 v37, 16, v111
	v_rcp_f32_e32 v36, v170
	s_add_u32 s8, s3, s42
	v_add_f32_e32 v32, 1.0, v32
	v_rcp_f32_e32 v35, v32
	v_mul_f32_e32 v28, v36, v28
	s_addc_u32 s9, s51, 0
	v_lshl_add_u64 v[32:33], s[8:9], 0, v[148:149]
	v_mul_f32_e32 v34, v35, v34
	v_mul_f32_e32 v35, 0xbfb8aa3b, v37
	v_exp_f32_e32 v35, v35
	v_mul_f32_e32 v28, v34, v28
	v_mov_b32_e32 v111, v67
	v_cvt_pk_bf16_f32 v28, v28, s0
	v_add_f32_e32 v34, 1.0, v35
	v_rcp_f32_e32 v38, v34
	v_lshl_add_u64 v[34:35], v[32:33], 0, v[110:111]
	global_store_short v[34:35], v28, off
	v_mul_f32_e32 v24, v36, v24
	v_mul_f32_e32 v28, v38, v37
	s_waitcnt vmcnt(30)
	v_lshlrev_b32_e32 v37, 16, v212
	v_mul_f32_e32 v38, 0xbfb8aa3b, v37
	v_exp_f32_e32 v38, v38
	v_mul_f32_e32 v24, v28, v24
	v_cvt_pk_bf16_f32 v24, v24, s0
	global_store_short v[34:35], v24, off offset:32
	v_add_f32_e32 v24, 1.0, v38
	s_waitcnt vmcnt(30)
	v_lshlrev_b32_e32 v28, 16, v89
	v_rcp_f32_e32 v24, v24
	v_mul_f32_e32 v38, 0xbfb8aa3b, v28
	v_exp_f32_e32 v38, v38
	v_mul_f32_e32 v20, v36, v20
	v_mul_f32_e32 v24, v24, v37
	v_mul_f32_e32 v20, v24, v20
	v_add_f32_e32 v24, 1.0, v38
	v_rcp_f32_e32 v24, v24
	v_cvt_pk_bf16_f32 v20, v20, s0
	global_store_short v[34:35], v20, off offset:64
	v_mul_f32_e32 v16, v36, v16
	v_mul_f32_e32 v20, v24, v28
	s_waitcnt vmcnt(30)
	v_lshlrev_b32_e32 v24, 16, v211
	v_mul_f32_e32 v28, 0xbfb8aa3b, v24
	v_exp_f32_e32 v28, v28
	v_mul_f32_e32 v16, v20, v16
	v_rcp_f32_e32 v20, v171
	v_mov_b32_e32 v89, v67
	v_cvt_pk_bf16_f32 v16, v16, s0
	v_lshl_add_u64 v[32:33], v[32:33], 0, v[88:89]
	v_add_f32_e32 v28, 1.0, v28
	s_waitcnt vmcnt(29)
	v_lshlrev_b32_e32 v34, 16, v210
	global_store_short v[32:33], v16, off
	v_mul_f32_e32 v16, v20, v29
	v_rcp_f32_e32 v28, v28
	v_mul_f32_e32 v29, 0xbfb8aa3b, v34
	v_exp_f32_e32 v29, v29
	v_lshl_add_u64 v[32:33], s[8:9], 0, v[150:151]
	v_mul_f32_e32 v24, v28, v24
	v_mul_f32_e32 v16, v24, v16
	v_add_f32_e32 v24, 1.0, v29
	v_rcp_f32_e32 v24, v24
	v_cvt_pk_bf16_f32 v16, v16, s0
	v_lshl_add_u64 v[28:29], v[32:33], 0, v[110:111]
	global_store_short v[28:29], v16, off
	v_mul_f32_e32 v16, v20, v25
	s_waitcnt vmcnt(30)
	v_lshlrev_b32_e32 v25, 16, v203
	v_mul_f32_e32 v24, v24, v34
	v_mul_f32_e32 v34, 0xbfb8aa3b, v25
	v_exp_f32_e32 v34, v34
	v_mul_f32_e32 v16, v24, v16
	v_cvt_pk_bf16_f32 v16, v16, s0
	global_store_short v[28:29], v16, off offset:32
	v_add_f32_e32 v16, 1.0, v34
	s_waitcnt vmcnt(30)
	v_lshlrev_b32_e32 v24, 16, v202
	v_rcp_f32_e32 v16, v16
	v_mul_f32_e32 v34, 0xbfb8aa3b, v24
	v_exp_f32_e32 v34, v34
	v_mul_f32_e32 v21, v20, v21
	v_mul_f32_e32 v16, v16, v25
	v_mul_f32_e32 v16, v16, v21
	v_add_f32_e32 v21, 1.0, v34
	v_rcp_f32_e32 v21, v21
	v_cvt_pk_bf16_f32 v16, v16, s0
	global_store_short v[28:29], v16, off offset:64
	v_mul_f32_e32 v16, v20, v17
	v_mul_f32_e32 v17, v21, v24
	s_waitcnt vmcnt(30)
	v_lshlrev_b32_e32 v21, 16, v201
	v_mul_f32_e32 v25, 0xbfb8aa3b, v21
	v_exp_f32_e32 v25, v25
	v_rcp_f32_e32 v24, v168
	s_waitcnt vmcnt(29)
; __device__ __forceinline__ unsigned f2bf(float f) { return pk2(f, 0.f) & 0xffffu; }
; __device__ __forceinline__ float siluf_(float x) { return x * __builtin_amdgcn_rcpf(1.f + __expf(-x)); }
; __device__ __forceinline__ void attn_prompt_item(const Args& A, LAS unsigned char* lds, int tid, int lane, int wave, int b, int nb, int kvh) {
;     ...
; #pragma unroll
;         for (int mt = 0; mt < 2; ++mt)
; #pragma unroll
;             for (int j = 0; j < 4; ++j) {
;                 const int tq = tt * 32 + mt * 16 + q4 * 4 + j; const size_t row = (size_t)b * SEQ + nb * 128 + tq; const float il = __builtin_amdgcn_rcpf(lrow[mt][j]);
; #pragma unroll
;                 for (int dt = 0; dt < 4; ++dt) { const int d = dt * 16 + fr; const float g = bf2f(gts[mt][j][dt]);
;                     MIX[row * DM + 512 + hq * 64 + d] = (bf16_t)f2bf(O[mt][dt][j] * il * siluf_(g)); }
;             }
	v_lshlrev_b32_e32 v28, 16, v200
	v_mul_f32_e32 v29, 0xbfb8aa3b, v28
	v_add_f32_e32 v25, 1.0, v25
	v_rcp_f32_e32 v25, v25
	v_mul_f32_e32 v16, v17, v16
	v_exp_f32_e32 v29, v29
	v_cvt_pk_bf16_f32 v20, v16, s0
	v_lshl_add_u64 v[16:17], v[32:33], 0, v[88:89]
	global_store_short v[16:17], v20, off
	v_mul_f32_e32 v20, v24, v30
	v_mul_f32_e32 v21, v25, v21
	v_mul_f32_e32 v20, v21, v20
	v_cvt_pk_bf16_f32 v25, v20, s0
	v_add_f32_e32 v20, 1.0, v29
	v_rcp_f32_e32 v29, v20
	v_lshl_add_u64 v[16:17], s[8:9], 0, v[152:153]
	v_lshl_add_u64 v[20:21], v[16:17], 0, v[110:111]
	global_store_short v[20:21], v25, off
	v_mul_f32_e32 v25, v24, v26
	v_mul_f32_e32 v26, v29, v28
	s_waitcnt vmcnt(30)
	v_lshlrev_b32_e32 v28, 16, v199
	v_mul_f32_e32 v29, 0xbfb8aa3b, v28
	v_exp_f32_e32 v29, v29
	v_mul_f32_e32 v25, v26, v25
	v_cvt_pk_bf16_f32 v25, v25, s0
	global_store_short v[20:21], v25, off offset:32
	v_add_f32_e32 v25, 1.0, v29
	s_waitcnt vmcnt(30)
	v_lshlrev_b32_e32 v26, 16, v198
	v_rcp_f32_e32 v25, v25
	v_mul_f32_e32 v29, 0xbfb8aa3b, v26
	v_exp_f32_e32 v29, v29
	v_mul_f32_e32 v22, v24, v22
	v_mul_f32_e32 v25, v25, v28
	v_mul_f32_e32 v22, v25, v22
	v_add_f32_e32 v25, 1.0, v29
	v_rcp_f32_e32 v25, v25
	v_cvt_pk_bf16_f32 v22, v22, s0
	global_store_short v[20:21], v22, off offset:64
	v_mul_f32_e32 v18, v24, v18
	v_mul_f32_e32 v20, v25, v26
	v_mul_f32_e32 v18, v20, v18
	s_waitcnt vmcnt(30)
	v_lshlrev_b32_e32 v20, 16, v197
	v_mul_f32_e32 v21, 0xbfb8aa3b, v20
	v_exp_f32_e32 v21, v21
	s_waitcnt vmcnt(29)
	v_lshlrev_b32_e32 v24, 16, v196
	v_rcp_f32_e32 v22, v169
	v_mul_f32_e32 v25, 0xbfb8aa3b, v24
	v_add_f32_e32 v21, 1.0, v21
	v_rcp_f32_e32 v21, v21
	v_exp_f32_e32 v25, v25
	v_cvt_pk_bf16_f32 v18, v18, s0
	v_lshl_add_u64 v[16:17], v[16:17], 0, v[88:89]
	global_store_short v[16:17], v18, off
	v_mul_f32_e32 v18, v22, v31
	v_mul_f32_e32 v20, v21, v20
	v_mul_f32_e32 v18, v20, v18
	v_add_f32_e32 v20, 1.0, v25
	v_rcp_f32_e32 v25, v20
	v_lshl_add_u64 v[16:17], s[8:9], 0, v[154:155]
	v_cvt_pk_bf16_f32 v18, v18, s0
	v_lshl_add_u64 v[20:21], v[16:17], 0, v[110:111]
	v_mul_f32_e32 v24, v25, v24
	s_waitcnt vmcnt(29)
	v_lshlrev_b32_e32 v25, 16, v195
	v_mul_f32_e32 v26, 0xbfb8aa3b, v25
	v_exp_f32_e32 v26, v26
	global_store_short v[20:21], v18, off
	v_mul_f32_e32 v18, v22, v27
	v_mul_f32_e32 v18, v24, v18
	v_cvt_pk_bf16_f32 v18, v18, s0
	global_store_short v[20:21], v18, off offset:32
	v_add_f32_e32 v18, 1.0, v26
	s_waitcnt vmcnt(30)
	v_lshlrev_b32_e32 v24, 16, v194
	v_rcp_f32_e32 v18, v18
	v_mul_f32_e32 v26, 0xbfb8aa3b, v24
	v_exp_f32_e32 v26, v26
	v_mul_f32_e32 v23, v22, v23
	v_mul_f32_e32 v18, v18, v25
	v_mul_f32_e32 v18, v18, v23
	v_add_f32_e32 v23, 1.0, v26
	v_rcp_f32_e32 v23, v23
	v_cvt_pk_bf16_f32 v18, v18, s0
	global_store_short v[20:21], v18, off offset:64
	v_mul_f32_e32 v18, v22, v19
	v_mul_f32_e32 v19, v23, v24
	v_mul_f32_e32 v18, v19, v18
	s_waitcnt vmcnt(30)
	v_lshlrev_b32_e32 v19, 16, v193
	v_mul_f32_e32 v21, 0xbfb8aa3b, v19
	v_exp_f32_e32 v21, v21
	v_cvt_pk_bf16_f32 v18, v18, s0
	v_lshl_add_u64 v[16:17], v[16:17], 0, v[88:89]
	global_store_short v[16:17], v18, off
	v_add_f32_e32 v18, 1.0, v21
	s_waitcnt vmcnt(30)
	v_lshlrev_b32_e32 v21, 16, v192
	v_rcp_f32_e32 v20, v166
	v_rcp_f32_e32 v18, v18
	v_mul_f32_e32 v22, 0xbfb8aa3b, v21
	v_exp_f32_e32 v22, v22
	v_mul_f32_e32 v12, v20, v12
	v_mul_f32_e32 v18, v18, v19
	v_mul_f32_e32 v12, v18, v12
	v_add_f32_e32 v18, 1.0, v22
	v_rcp_f32_e32 v22, v18
	v_lshl_add_u64 v[16:17], s[8:9], 0, v[156:157]
	v_cvt_pk_bf16_f32 v12, v12, s0
	v_lshl_add_u64 v[18:19], v[16:17], 0, v[110:111]
	global_store_short v[18:19], v12, off
	v_mul_f32_e32 v12, v22, v21
	s_waitcnt vmcnt(30)
	v_lshlrev_b32_e32 v21, 16, v191
	v_mul_f32_e32 v22, 0xbfb8aa3b, v21
	v_exp_f32_e32 v22, v22
	v_mul_f32_e32 v8, v20, v8
	v_mul_f32_e32 v8, v12, v8
	v_cvt_pk_bf16_f32 v8, v8, s0
	global_store_short v[18:19], v8, off offset:32
	v_add_f32_e32 v8, 1.0, v22
	s_waitcnt vmcnt(30)
	v_lshlrev_b32_e32 v12, 16, v190
	v_rcp_f32_e32 v8, v8
	v_mul_f32_e32 v22, 0xbfb8aa3b, v12
	v_exp_f32_e32 v22, v22
	v_mul_f32_e32 v4, v20, v4
	v_mul_f32_e32 v8, v8, v21
	v_mul_f32_e32 v4, v8, v4
	v_add_f32_e32 v8, 1.0, v22
	v_rcp_f32_e32 v8, v8
	v_cvt_pk_bf16_f32 v4, v4, s0
	global_store_short v[18:19], v4, off offset:64
	v_mul_f32_e32 v0, v20, v0
	v_mul_f32_e32 v4, v8, v12
	s_waitcnt vmcnt(30)
; __device__ __forceinline__ unsigned f2bf(float f) { return pk2(f, 0.f) & 0xffffu; }
; __device__ __forceinline__ float siluf_(float x) { return x * __builtin_amdgcn_rcpf(1.f + __expf(-x)); }
; __device__ __forceinline__ void attn_prompt_item(const Args& A, LAS unsigned char* lds, int tid, int lane, int wave, int b, int nb, int kvh) {
;     ...
; #pragma unroll
;         for (int mt = 0; mt < 2; ++mt)
; #pragma unroll
;             for (int j = 0; j < 4; ++j) {
;                 const int tq = tt * 32 + mt * 16 + q4 * 4 + j; const size_t row = (size_t)b * SEQ + nb * 128 + tq; const float il = __builtin_amdgcn_rcpf(lrow[mt][j]);
; #pragma unroll
;                 for (int dt = 0; dt < 4; ++dt) { const int d = dt * 16 + fr; const float g = bf2f(gts[mt][j][dt]);
;                     MIX[row * DM + 512 + hq * 64 + d] = (bf16_t)f2bf(O[mt][dt][j] * il * siluf_(g)); }
;             }
;     }
	v_lshlrev_b32_e32 v8, 16, v189
	v_mul_f32_e32 v12, 0xbfb8aa3b, v8
	v_exp_f32_e32 v12, v12
	v_mul_f32_e32 v0, v4, v0
	v_rcp_f32_e32 v4, v167
	v_cvt_pk_bf16_f32 v0, v0, s0
	v_lshl_add_u64 v[16:17], v[16:17], 0, v[88:89]
	v_add_f32_e32 v12, 1.0, v12
	s_waitcnt vmcnt(29)
	v_lshlrev_b32_e32 v18, 16, v188
	global_store_short v[16:17], v0, off
	v_mul_f32_e32 v0, v4, v13
	v_rcp_f32_e32 v12, v12
	v_mul_f32_e32 v13, 0xbfb8aa3b, v18
	v_exp_f32_e32 v13, v13
	v_lshl_add_u64 v[16:17], s[8:9], 0, v[158:159]
	v_mul_f32_e32 v8, v12, v8
	v_mul_f32_e32 v0, v8, v0
	v_add_f32_e32 v8, 1.0, v13
	v_rcp_f32_e32 v8, v8
	v_cvt_pk_bf16_f32 v0, v0, s0
	v_lshl_add_u64 v[12:13], v[16:17], 0, v[110:111]
	global_store_short v[12:13], v0, off
	v_mul_f32_e32 v0, v4, v9
	s_waitcnt vmcnt(30)
	v_lshlrev_b32_e32 v9, 16, v187
	v_mul_f32_e32 v8, v8, v18
	v_mul_f32_e32 v18, 0xbfb8aa3b, v9
	v_exp_f32_e32 v18, v18
	v_mul_f32_e32 v0, v8, v0
	v_cvt_pk_bf16_f32 v0, v0, s0
	global_store_short v[12:13], v0, off offset:32
	v_add_f32_e32 v0, 1.0, v18
	s_waitcnt vmcnt(30)
	v_lshlrev_b32_e32 v8, 16, v186
	v_rcp_f32_e32 v0, v0
	v_mul_f32_e32 v18, 0xbfb8aa3b, v8
	v_exp_f32_e32 v18, v18
	v_mul_f32_e32 v5, v4, v5
	v_mul_f32_e32 v0, v0, v9
	v_mul_f32_e32 v0, v0, v5
	v_add_f32_e32 v5, 1.0, v18
	v_rcp_f32_e32 v5, v5
	v_cvt_pk_bf16_f32 v0, v0, s0
	global_store_short v[12:13], v0, off offset:64
	v_mul_f32_e32 v0, v4, v1
	v_mul_f32_e32 v1, v5, v8
	s_waitcnt vmcnt(30)
	v_lshlrev_b32_e32 v5, 16, v185
	v_mul_f32_e32 v9, 0xbfb8aa3b, v5
	v_exp_f32_e32 v9, v9
	v_rcp_f32_e32 v8, v164
	s_waitcnt vmcnt(29)
	v_lshlrev_b32_e32 v12, 16, v184
	v_mul_f32_e32 v13, 0xbfb8aa3b, v12
	v_add_f32_e32 v9, 1.0, v9
	v_rcp_f32_e32 v9, v9
	v_mul_f32_e32 v0, v1, v0
	v_exp_f32_e32 v13, v13
	v_cvt_pk_bf16_f32 v4, v0, s0
	v_lshl_add_u64 v[0:1], v[16:17], 0, v[88:89]
	global_store_short v[0:1], v4, off
	v_mul_f32_e32 v4, v8, v14
	v_mul_f32_e32 v5, v9, v5
	v_mul_f32_e32 v4, v5, v4
	v_cvt_pk_bf16_f32 v9, v4, s0
	v_add_f32_e32 v4, 1.0, v13
	v_rcp_f32_e32 v13, v4
	v_lshl_add_u64 v[0:1], s[8:9], 0, v[160:161]
	v_lshl_add_u64 v[4:5], v[0:1], 0, v[110:111]
	global_store_short v[4:5], v9, off
	v_mul_f32_e32 v9, v8, v10
	v_mul_f32_e32 v10, v13, v12
	s_waitcnt vmcnt(30)
	v_lshlrev_b32_e32 v12, 16, v183
	v_mul_f32_e32 v13, 0xbfb8aa3b, v12
	v_exp_f32_e32 v13, v13
	v_mul_f32_e32 v9, v10, v9
	v_cvt_pk_bf16_f32 v9, v9, s0
	global_store_short v[4:5], v9, off offset:32
	v_add_f32_e32 v9, 1.0, v13
	s_waitcnt vmcnt(30)
	v_lshlrev_b32_e32 v10, 16, v182
	v_rcp_f32_e32 v9, v9
	v_mul_f32_e32 v13, 0xbfb8aa3b, v10
	v_exp_f32_e32 v13, v13
	v_mul_f32_e32 v6, v8, v6
	v_mul_f32_e32 v9, v9, v12
	v_mul_f32_e32 v6, v9, v6
	v_add_f32_e32 v9, 1.0, v13
	v_rcp_f32_e32 v9, v9
	v_cvt_pk_bf16_f32 v6, v6, s0
	global_store_short v[4:5], v6, off offset:64
	v_mul_f32_e32 v2, v8, v2
	v_mul_f32_e32 v4, v9, v10
	v_mul_f32_e32 v2, v4, v2
	s_waitcnt vmcnt(30)
	v_lshlrev_b32_e32 v4, 16, v181
	v_mul_f32_e32 v5, 0xbfb8aa3b, v4
	v_exp_f32_e32 v5, v5
	s_waitcnt vmcnt(29)
	v_lshlrev_b32_e32 v8, 16, v180
	v_rcp_f32_e32 v6, v165
	v_mul_f32_e32 v9, 0xbfb8aa3b, v8
	v_add_f32_e32 v5, 1.0, v5
	v_rcp_f32_e32 v5, v5
	v_exp_f32_e32 v9, v9
	v_cvt_pk_bf16_f32 v2, v2, s0
	v_lshl_add_u64 v[0:1], v[0:1], 0, v[88:89]
	global_store_short v[0:1], v2, off
	v_mul_f32_e32 v2, v6, v15
	v_mul_f32_e32 v4, v5, v4
	v_mul_f32_e32 v2, v4, v2
	v_add_f32_e32 v4, 1.0, v9
	v_rcp_f32_e32 v9, v4
	v_lshl_add_u64 v[0:1], s[8:9], 0, v[162:163]
	v_cvt_pk_bf16_f32 v2, v2, s0
	v_lshl_add_u64 v[4:5], v[0:1], 0, v[110:111]
	v_mul_f32_e32 v8, v9, v8
	s_waitcnt vmcnt(29)
	v_lshlrev_b32_e32 v9, 16, v179
	v_mul_f32_e32 v10, 0xbfb8aa3b, v9
	v_exp_f32_e32 v10, v10
	global_store_short v[4:5], v2, off
	v_mul_f32_e32 v2, v6, v11
	v_mul_f32_e32 v2, v8, v2
	v_cvt_pk_bf16_f32 v2, v2, s0
	global_store_short v[4:5], v2, off offset:32
	v_add_f32_e32 v2, 1.0, v10
	s_waitcnt vmcnt(30)
	v_lshlrev_b32_e32 v8, 16, v66
	v_rcp_f32_e32 v2, v2
	v_mul_f32_e32 v10, 0xbfb8aa3b, v8
	v_exp_f32_e32 v10, v10
	v_mul_f32_e32 v7, v6, v7
	v_mul_f32_e32 v2, v2, v9
	v_mul_f32_e32 v2, v2, v7
	v_add_f32_e32 v7, 1.0, v10
	v_rcp_f32_e32 v7, v7
	v_cvt_pk_bf16_f32 v2, v2, s0
	global_store_short v[4:5], v2, off offset:64
	v_mul_f32_e32 v2, v6, v3
	v_mul_f32_e32 v3, v7, v8
	v_mul_f32_e32 v2, v3, v2
	s_add_i32 s8, s65, 8
	v_cvt_pk_bf16_f32 v2, v2, s0
	v_lshl_add_u64 v[0:1], v[0:1], 0, v[88:89]
	s_cmp_gt_u32 s65, 7
	s_mov_b32 s65, s8
	global_store_short v[0:1], v2, off
	s_cbranch_scc0 .LBB0_307
	s_branch .LBB0_288
